# next ticket published at the selection-closing barrier; q rows and head weights requested with the K tiles right after the attention loop
# speedup vs baseline: 1.0150x; 1.0025x over previous
.LBB0_507:
	s_or_b64 exec, exec, s[38:39]
	v_add_u32_e32 v0, v172, v192
	v_lshl_add_u32 v0, v0, 5, 0
	v_add_u32_e32 v4, 0x23000, v0
	v_mov_b32_e32 v0, v169
	s_and_saveexec_b64 s[98:99], s[8:9]
	s_cbranch_execz .Lkq_nw
	v_mov_b32_e32 v222, s86
	ds_write_b32 v222, v196
.Lkq_nw:
	s_or_b64 exec, exec, s[98:99]
	s_waitcnt lgkmcnt(0)
	s_barrier
	v_min_i32_e32 v173, 0xff, v160
	v_mov_b32_e32 v1, v0
	v_mov_b32_e32 v2, v0
	v_mov_b32_e32 v3, v0
	ds_write_b128 v4, v[0:3]
	ds_write_b128 v4, v[0:3] offset:16
	v_add_u32_e32 v1, 32, v173
	v_lshrrev_b32_e32 v1, 5, v1
	v_add_u32_e32 v2, 1, v1
	v_and_b32_e32 v163, 15, v172
	v_lshrrev_b32_e32 v2, 1, v2
	v_ashrrev_i32_e32 v165, 4, v172
	v_mov_b32_e32 v161, v169
	v_lshlrev_b32_e32 v0, 8, v163
	v_cndmask_b32_e64 v197, v2, 0, s[40:41]
	v_cndmask_b32_e64 v177, v1, v2, s[40:41]
	v_mov_b32_e32 v3, 0
	v_lshlrev_b64 v[174:175], 12, v[160:161]
	v_lshlrev_b32_e32 v176, 2, v165
	v_cmp_lt_u32_e32 vcc, v197, v177
	v_mov_b32_e32 v204, 0xff800000
	v_lshlrev_b32_e32 v168, 1, v0
	v_mov_b32_e32 v2, v3
	v_mov_b32_e32 v1, v3
	v_mov_b32_e32 v0, v3
	v_mov_b32_e32 v7, v3
	v_mov_b32_e32 v6, v3
	v_mov_b32_e32 v5, v3
	v_mov_b32_e32 v4, v3
	v_mov_b32_e32 v11, v3
	v_mov_b32_e32 v10, v3
	v_mov_b32_e32 v9, v3
	v_mov_b32_e32 v8, v3
	v_mov_b32_e32 v15, v3
	v_mov_b32_e32 v14, v3
	v_mov_b32_e32 v13, v3
	v_mov_b32_e32 v12, v3
	s_waitcnt vmcnt(3)
	v_mov_b32_e32 v63, v3
	v_mov_b32_e32 v62, v3
	v_mov_b32_e32 v61, v3
	v_mov_b32_e32 v60, v3
	s_waitcnt vmcnt(2)
	v_mov_b32_e32 v59, v3
	v_mov_b32_e32 v58, v3
	v_mov_b32_e32 v57, v3
	v_mov_b32_e32 v56, v3
	s_waitcnt vmcnt(1)
	v_mov_b32_e32 v55, v3
	v_mov_b32_e32 v54, v3
	v_mov_b32_e32 v53, v3
	v_mov_b32_e32 v52, v3
	s_waitcnt vmcnt(0)
	v_mov_b32_e32 v51, v3
	v_mov_b32_e32 v50, v3
	v_mov_b32_e32 v49, v3
	v_mov_b32_e32 v48, v3
	v_mov_b32_e32 v47, v3
	v_mov_b32_e32 v46, v3
	v_mov_b32_e32 v45, v3
	v_mov_b32_e32 v44, v3
	v_mov_b32_e32 v43, v3
	v_mov_b32_e32 v42, v3
	v_mov_b32_e32 v41, v3
	v_mov_b32_e32 v40, v3
	v_mov_b32_e32 v39, v3
	v_mov_b32_e32 v38, v3
	v_mov_b32_e32 v37, v3
	v_mov_b32_e32 v36, v3
	v_mov_b32_e32 v35, v3
	v_mov_b32_e32 v34, v3
	v_mov_b32_e32 v33, v3
	v_mov_b32_e32 v32, v3
	v_mov_b32_e32 v31, v3
	v_mov_b32_e32 v30, v3
	v_mov_b32_e32 v29, v3
	v_mov_b32_e32 v28, v3
	v_mov_b32_e32 v27, v3
	v_mov_b32_e32 v26, v3
	v_mov_b32_e32 v25, v3
	v_mov_b32_e32 v24, v3
	v_mov_b32_e32 v23, v3
	v_mov_b32_e32 v22, v3
	v_mov_b32_e32 v21, v3
	v_mov_b32_e32 v20, v3
	v_mov_b32_e32 v19, v3
	v_mov_b32_e32 v18, v3
	v_mov_b32_e32 v17, v3
	v_mov_b32_e32 v16, v3
	v_mov_b32_e32 v164, v3
	s_and_saveexec_b64 s[0:1], vcc
	s_cbranch_execz .LBB0_513
	v_readlane_b32 s36, v250, 48
	v_readlane_b32 s37, v250, 49
	v_lshlrev_b32_e32 v2, 3, v165
	v_ashrrev_i32_e32 v3, 31, v2
	v_lshl_add_u64 v[0:1], v[174:175], 1, s[36:37]
	v_lshl_add_u64 v[0:1], v[0:1], 0, v[168:169]
	v_lshlrev_b64 v[2:3], 1, v[2:3]
	v_lshl_add_u32 v198, v163, 2, v186
	v_lshl_add_u64 v[0:1], v[0:1], 0, v[2:3]
	v_lshl_add_u32 v4, v197, 7, v198
	ds_read2_b32 v[4:5], v4 offset1:16
	v_readlane_b32 s36, v250, 44
	v_readlane_b32 s37, v250, 45
	v_mov_b32_e32 v205, 0
	s_mov_b32 s100, s36
	s_mov_b32 s101, s37
	v_and_b32_e32 v224, 31, v172
	v_lshlrev_b32_e32 v224, 4, v224
	v_lshrrev_b32_e32 v225, 5, v172
	v_mul_u32_u24_e32 v226, 0x2200, v225
	v_add3_u32 v226, v226, v224, v193
	v_lshl_add_u32 v225, v225, 6, v186
	v_lshl_add_u32 v227, v197, 7, v225
	v_mov_b32_e32 v228, 0xff800000
	ds_read_b128 v[234:237], v227
	ds_read_b128 v[238:241], v227 offset:16
	ds_read_b128 v[242:245], v227 offset:32
	ds_read_b128 v[246:249], v227 offset:48
	s_waitcnt lgkmcnt(0)
	v_lshl_add_u32 v234, v234, 9, v224
	v_lshl_add_u32 v235, v235, 9, v224
	v_lshl_add_u32 v236, v236, 9, v224
	v_lshl_add_u32 v237, v237, 9, v224
	v_lshl_add_u32 v238, v238, 9, v224
	v_lshl_add_u32 v239, v239, 9, v224
	v_lshl_add_u32 v240, v240, 9, v224
	v_lshl_add_u32 v241, v241, 9, v224
	v_lshl_add_u32 v242, v242, 9, v224
	v_lshl_add_u32 v243, v243, 9, v224
	v_lshl_add_u32 v244, v244, 9, v224
	v_lshl_add_u32 v245, v245, 9, v224
	v_lshl_add_u32 v246, v246, 9, v224
	v_lshl_add_u32 v247, v247, 9, v224
	v_lshl_add_u32 v248, v248, 9, v224
	v_lshl_add_u32 v249, v249, 9, v224
	global_load_dwordx4 v[96:99], v234, s[100:101]
	global_load_dwordx4 v[100:103], v235, s[100:101]
	global_load_dwordx4 v[104:107], v236, s[100:101]
	global_load_dwordx4 v[108:111], v237, s[100:101]
	global_load_dwordx4 v[112:115], v238, s[100:101]
	global_load_dwordx4 v[116:119], v239, s[100:101]
	global_load_dwordx4 v[120:123], v240, s[100:101]
	global_load_dwordx4 v[124:127], v241, s[100:101]
	global_load_dwordx4 v[128:131], v242, s[100:101]
	global_load_dwordx4 v[132:135], v243, s[100:101]
	global_load_dwordx4 v[136:139], v244, s[100:101]
	global_load_dwordx4 v[140:143], v245, s[100:101]
	global_load_dwordx4 v[144:147], v246, s[100:101]
	global_load_dwordx4 v[148:151], v247, s[100:101]
	global_load_dwordx4 v[152:155], v248, s[100:101]
	global_load_dwordx4 v[156:159], v249, s[100:101]
	v_lshrrev_b32_e32 v0, 2, v163
	v_or_b32_e32 v0, v176, v0
	s_movk_i32 s36, 0x110
	v_mul_lo_u32 v0, v0, s36
	v_and_or_b32 v0, v162, 12, v0
	v_lshl_add_u32 v200, v0, 1, v193
	v_lshl_add_u32 v0, v165, 4, v193
	v_mul_u32_u24_e32 v1, 0x220, v163
	v_cmp_gt_i32_e32 vcc, s16, v160
	v_xor_b32_e32 v199, 0x80, v162
	v_xor_b32_e32 v201, 64, v162
	v_lshl_add_u32 v202, v197, 5, v176
	v_mov_b32_e32 v206, 0xff800000
	s_mov_b64 s[38:39], 0
	v_add_u32_e32 v203, v0, v1
	v_mov_b32_e32 v16, 0
	v_mov_b32_e32 v17, v205
	v_mov_b32_e32 v18, v205
	v_mov_b32_e32 v19, v205
	v_mov_b32_e32 v20, 0
	v_mov_b32_e32 v21, v205
	v_mov_b32_e32 v22, v205
	v_mov_b32_e32 v23, v205
	v_mov_b32_e32 v24, 0
	v_mov_b32_e32 v25, v205
	v_mov_b32_e32 v26, v205
	v_mov_b32_e32 v27, v205
	v_mov_b32_e32 v28, 0
	v_mov_b32_e32 v29, v205
	v_mov_b32_e32 v30, v205
	v_mov_b32_e32 v31, v205
	v_mov_b32_e32 v32, 0
	v_mov_b32_e32 v33, v205
	v_mov_b32_e32 v34, v205
	v_mov_b32_e32 v35, v205
	v_mov_b32_e32 v36, 0
	v_mov_b32_e32 v37, v205
	v_mov_b32_e32 v38, v205
	v_mov_b32_e32 v39, v205
	v_mov_b32_e32 v40, 0
	v_mov_b32_e32 v41, v205
	v_mov_b32_e32 v42, v205
	v_mov_b32_e32 v43, v205
	v_mov_b32_e32 v44, 0
	v_mov_b32_e32 v45, v205
	v_mov_b32_e32 v46, v205
	v_mov_b32_e32 v47, v205
	v_mov_b32_e32 v48, 0
	v_mov_b32_e32 v49, v205
	v_mov_b32_e32 v50, v205
	v_mov_b32_e32 v51, v205
	v_mov_b32_e32 v52, 0
	v_mov_b32_e32 v53, v205
	v_mov_b32_e32 v54, v205
	v_mov_b32_e32 v55, v205
	v_mov_b32_e32 v56, 0
	v_mov_b32_e32 v57, v205
	v_mov_b32_e32 v58, v205
	v_mov_b32_e32 v59, v205
	v_mov_b32_e32 v60, 0
	v_mov_b32_e32 v61, v205
	v_mov_b32_e32 v62, v205
	v_mov_b32_e32 v63, v205
	v_mov_b32_e32 v12, 0
	v_mov_b32_e32 v13, v205
	v_mov_b32_e32 v14, v205
	v_mov_b32_e32 v15, v205
	v_mov_b32_e32 v8, 0
	v_mov_b32_e32 v9, v205
	v_mov_b32_e32 v10, v205
	v_mov_b32_e32 v11, v205
	v_mov_b32_e32 v4, 0
	v_mov_b32_e32 v5, v205
	v_mov_b32_e32 v6, v205
	v_mov_b32_e32 v7, v205
	v_mov_b32_e32 v0, 0
	v_mov_b32_e32 v1, v205
	v_mov_b32_e32 v2, v205
	v_mov_b32_e32 v3, v205
	s_branch .LBB0_510

.LBB0_513:
	s_or_b64 exec, exec, s[0:1]
	v_readlane_b32 s98, v250, 46
	v_readlane_b32 s99, v250, 47
	v_and_b32_e32 v222, 63, v171
	v_lshrrev_b32_e32 v223, 6, v171
	v_lshlrev_b32_e32 v222, 4, v222
	v_lshl_add_u32 v222, v223, 12, v222
	s_nop 1
	global_load_dwordx4 v[80:83], v222, s[98:99]
	global_load_dwordx4 v[84:87], v222, s[98:99] offset:1024
	global_load_dwordx4 v[88:91], v222, s[98:99] offset:2048
	global_load_dwordx4 v[92:95], v222, s[98:99] offset:3072
	s_add_u32 s98, s98, 0x8000
	s_addc_u32 s99, s99, 0
	global_load_dwordx4 v[206:209], v222, s[98:99]
	global_load_dwordx4 v[210:213], v222, s[98:99] offset:1024
	global_load_dwordx4 v[214:217], v222, s[98:99] offset:2048
	global_load_dwordx4 v[218:221], v222, s[98:99] offset:3072
	v_mov_b32_e32 v222, s86
	ds_read_b32 v223, v222
	s_waitcnt lgkmcnt(0)
	v_readfirstlane_b32 s98, v223
	s_cmpk_lt_i32 s98, 0x804
	s_cbranch_scc0 .Lkq_skip_b
	s_lshl_b32 s98, s98, 2
	s_sub_i32 s98, 0x200c, s98
	v_and_b32_e32 v222, 3, v184
	v_or_b32_e32 v222, s98, v222
	v_lshlrev_b32_e32 v222, 14, v222
	v_lshlrev_b32_e32 v223, 5, v184
	v_and_b32_e32 v223, 0x380, v223
	v_add_u32_e32 v222, v222, v223
	v_lshrrev_b32_e32 v223, 5, v184
	v_lshl_add_u32 v222, v223, 4, v222
	v_add_u32_e32 v222, 0x1200, v222
	v_mov_b32_e32 v223, s98
	v_lshlrev_b32_e32 v223, 14, v223
	v_add_u32_e32 v223, 0x1680, v223
	global_load_dwordx4 v[198:201], v222, s[50:51]
	global_load_dwordx4 v[244:247], v222, s[50:51] offset:32
	global_load_dwordx4 v[160:163], v222, s[50:51] offset:64
	global_load_dwordx4 v[176:179], v222, s[50:51] offset:96
	global_load_dwordx4 v[224:227], v223, s[50:51]
	v_add_u32_e32 v223, 0x4000, v223
	global_load_dwordx4 v[228:231], v223, s[50:51]
	v_add_u32_e32 v223, 0x4000, v223
	global_load_dwordx4 v[232:235], v223, s[50:51]
	v_add_u32_e32 v223, 0x4000, v223
	global_load_dwordx4 v[236:239], v223, s[50:51]
.Lkq_skip_b:
	s_mov_b64 s[0:1], exec
	v_readlane_b32 s36, v250, 52
	v_readlane_b32 s37, v250, 53
	s_and_b64 s[36:37], s[0:1], s[36:37]
	s_mov_b64 exec, s[36:37]
	s_cbranch_execz .LBB0_515
	v_lshl_add_u32 v64, v172, 2, v193
	ds_write2st64_b32 v64, v204, v164 offset1:1
	ds_write2st64_b32 v64, v60, v61 offset0:2 offset1:3
	ds_write2st64_b32 v64, v62, v63 offset0:4 offset1:5
	ds_write2st64_b32 v64, v56, v57 offset0:6 offset1:7
	ds_write2st64_b32 v64, v58, v59 offset0:8 offset1:9
	ds_write2st64_b32 v64, v52, v53 offset0:10 offset1:11
	ds_write2st64_b32 v64, v54, v55 offset0:12 offset1:13
	ds_write2st64_b32 v64, v48, v49 offset0:14 offset1:15
	ds_write2st64_b32 v64, v50, v51 offset0:16 offset1:17
	ds_write2st64_b32 v64, v44, v45 offset0:18 offset1:19
	ds_write2st64_b32 v64, v46, v47 offset0:20 offset1:21
	ds_write2st64_b32 v64, v40, v41 offset0:22 offset1:23
	ds_write2st64_b32 v64, v42, v43 offset0:24 offset1:25
	ds_write2st64_b32 v64, v36, v37 offset0:26 offset1:27
	ds_write2st64_b32 v64, v38, v39 offset0:28 offset1:29
	ds_write2st64_b32 v64, v32, v33 offset0:30 offset1:31
	ds_write2st64_b32 v64, v34, v35 offset0:32 offset1:33
	ds_write2st64_b32 v64, v28, v29 offset0:34 offset1:35
	ds_write2st64_b32 v64, v30, v31 offset0:36 offset1:37
	ds_write2st64_b32 v64, v24, v25 offset0:38 offset1:39
	ds_write2st64_b32 v64, v26, v27 offset0:40 offset1:41
	ds_write2st64_b32 v64, v20, v21 offset0:42 offset1:43
	ds_write2st64_b32 v64, v22, v23 offset0:44 offset1:45
	ds_write2st64_b32 v64, v16, v17 offset0:46 offset1:47
	ds_write2st64_b32 v64, v18, v19 offset0:48 offset1:49
	ds_write2st64_b32 v64, v12, v13 offset0:50 offset1:51
	ds_write2st64_b32 v64, v14, v15 offset0:52 offset1:53
	ds_write2st64_b32 v64, v8, v9 offset0:54 offset1:55
	ds_write2st64_b32 v64, v10, v11 offset0:56 offset1:57
	ds_write2st64_b32 v64, v4, v5 offset0:58 offset1:59
	ds_write2st64_b32 v64, v6, v7 offset0:60 offset1:61
	ds_write2st64_b32 v64, v0, v1 offset0:62 offset1:63
	ds_write2st64_b32 v64, v2, v3 offset0:64 offset1:65
.LBB0_515:
	s_or_b64 exec, exec, s[0:1]
	s_waitcnt lgkmcnt(0)
	s_barrier
	s_and_saveexec_b64 s[0:1], s[40:41]
	s_cbranch_execz .LBB0_517
	s_waitcnt vmcnt(16)
	v_lshl_add_u32 v67, v172, 2, v194
	ds_read2st64_b32 v[68:69], v67 offset1:1
	ds_read2st64_b32 v[96:97], v67 offset0:2 offset1:3
	ds_read2st64_b32 v[98:99], v67 offset0:4 offset1:5
	ds_read2st64_b32 v[100:101], v67 offset0:6 offset1:7
	ds_read2st64_b32 v[102:103], v67 offset0:8 offset1:9
	ds_read2st64_b32 v[104:105], v67 offset0:10 offset1:11
	ds_read2st64_b32 v[106:107], v67 offset0:12 offset1:13
	ds_read2st64_b32 v[108:109], v67 offset0:14 offset1:15
	ds_read2st64_b32 v[110:111], v67 offset0:16 offset1:17
	ds_read2st64_b32 v[112:113], v67 offset0:18 offset1:19
	ds_read2st64_b32 v[114:115], v67 offset0:20 offset1:21
	ds_read2st64_b32 v[116:117], v67 offset0:22 offset1:23
	ds_read2st64_b32 v[118:119], v67 offset0:24 offset1:25
	ds_read2st64_b32 v[120:121], v67 offset0:26 offset1:27
	ds_read2st64_b32 v[122:123], v67 offset0:28 offset1:29
	ds_read2st64_b32 v[124:125], v67 offset0:30 offset1:31
	ds_read2st64_b32 v[126:127], v67 offset0:32 offset1:33
	ds_read2st64_b32 v[128:129], v67 offset0:34 offset1:35
	ds_read2st64_b32 v[130:131], v67 offset0:36 offset1:37
	ds_read2st64_b32 v[132:133], v67 offset0:38 offset1:39
	ds_read2st64_b32 v[134:135], v67 offset0:40 offset1:41
	ds_read2st64_b32 v[136:137], v67 offset0:42 offset1:43
	ds_read2st64_b32 v[138:139], v67 offset0:44 offset1:45
	ds_read2st64_b32 v[140:141], v67 offset0:46 offset1:47
	ds_read2st64_b32 v[142:143], v67 offset0:48 offset1:49
	ds_read2st64_b32 v[144:145], v67 offset0:50 offset1:51
	ds_read2st64_b32 v[146:147], v67 offset0:52 offset1:53
	ds_read2st64_b32 v[148:149], v67 offset0:54 offset1:55
	ds_read2st64_b32 v[150:151], v67 offset0:56 offset1:57
	ds_read2st64_b32 v[152:153], v67 offset0:58 offset1:59
	ds_read2st64_b32 v[154:155], v67 offset0:60 offset1:61
	ds_read2st64_b32 v[156:157], v67 offset0:62 offset1:63
	ds_read2st64_b32 v[158:159], v67 offset0:64 offset1:65
	v_max_f32_e32 v70, v204, v204
	v_readlane_b32 s36, v250, 50
	v_readlane_b32 s37, v250, 51
	v_and_b32_e32 v75, 15, v172
	v_lshrrev_b32_e32 v76, 4, v172
	v_mul_u32_u24_e32 v75, 0x210, v75
	v_lshl_add_u32 v75, v76, 3, v75
	v_add_u32_e32 v75, v75, v193
	v_lshrrev_b32_e32 v76, 5, v172
	v_mul_u32_u24_e32 v76, 0x210, v76
	v_and_b32_e32 v77, 31, v172
	v_lshl_add_u32 v76, v77, 4, v76
	v_add_u32_e32 v76, v76, v193
	s_waitcnt lgkmcnt(0)
	v_max_f32_e32 v66, v68, v68
	v_max_f32_e32 v66, v70, v66
	v_sub_f32_e32 v70, v204, v66
	v_sub_f32_e32 v66, v68, v66
	v_exp_f32_e32 v70, v70
	v_exp_f32_e32 v71, v66
	v_mov_b32_e32 v165, v69
	v_lshl_add_u64 v[64:65], v[174:175], 1, s[36:37]
	v_lshlrev_b32_e32 v72, 4, v172
	v_mov_b32_e32 v73, 0
	v_pk_mul_f32 v[68:69], v[164:165], v[70:71]
	v_lshl_add_u64 v[64:65], v[64:65], 0, v[72:73]
	v_add_f32_e32 v66, v68, v69
	v_div_scale_f32 v68, s[36:37], v66, v66, 1.0
	v_rcp_f32_e32 v69, v68
	s_nop 0
	v_fma_f32 v72, -v68, v69, 1.0
	v_fmac_f32_e32 v69, v72, v69
	v_div_scale_f32 v72, vcc, 1.0, v66, 1.0
	v_mul_f32_e32 v73, v72, v69
	v_fma_f32 v74, -v68, v73, v72
	v_fmac_f32_e32 v73, v74, v69
	v_fma_f32 v68, -v68, v73, v72
	v_div_fmas_f32 v68, v68, v69, v73
	v_div_fixup_f32 v68, v68, v66, 1.0
	v_mul_f32_e32 v66, v70, v68
	v_mul_f32_e32 v68, v71, v68
	s_mov_b64 s[36:37], 0x1000
	v_lshl_add_u64 v[78:79], v[64:65], 0, s[36:37]
	v_pk_mul_f32 v[96:97], v[68:69], v[96:97] op_sel_hi:[0,1]
	v_pk_mul_f32 v[98:99], v[68:69], v[98:99] op_sel_hi:[0,1]
	v_pk_fma_f32 v[60:61], v[66:67], v[60:61], v[96:97] op_sel_hi:[0,1,1]
	v_pk_fma_f32 v[62:63], v[66:67], v[62:63], v[98:99] op_sel_hi:[0,1,1]
	v_cvt_pk_bf16_f32 v60, v60, v61
	v_cvt_pk_bf16_f32 v61, v62, v63
	ds_write_b64 v75, v[60:61]
	v_pk_mul_f32 v[100:101], v[68:69], v[100:101] op_sel_hi:[0,1]
	v_pk_mul_f32 v[102:103], v[68:69], v[102:103] op_sel_hi:[0,1]
	v_pk_fma_f32 v[56:57], v[66:67], v[56:57], v[100:101] op_sel_hi:[0,1,1]
	v_pk_fma_f32 v[58:59], v[66:67], v[58:59], v[102:103] op_sel_hi:[0,1,1]
	v_cvt_pk_bf16_f32 v56, v56, v57
	v_cvt_pk_bf16_f32 v57, v58, v59
	ds_write_b64 v75, v[56:57] offset:32
	v_pk_mul_f32 v[104:105], v[68:69], v[104:105] op_sel_hi:[0,1]
	v_pk_mul_f32 v[106:107], v[68:69], v[106:107] op_sel_hi:[0,1]
	v_pk_fma_f32 v[52:53], v[66:67], v[52:53], v[104:105] op_sel_hi:[0,1,1]
	v_pk_fma_f32 v[54:55], v[66:67], v[54:55], v[106:107] op_sel_hi:[0,1,1]
	v_cvt_pk_bf16_f32 v52, v52, v53
	v_cvt_pk_bf16_f32 v53, v54, v55
	ds_write_b64 v75, v[52:53] offset:64
	v_pk_mul_f32 v[108:109], v[68:69], v[108:109] op_sel_hi:[0,1]
	v_pk_mul_f32 v[110:111], v[68:69], v[110:111] op_sel_hi:[0,1]
	v_pk_fma_f32 v[48:49], v[66:67], v[48:49], v[108:109] op_sel_hi:[0,1,1]
	v_pk_fma_f32 v[50:51], v[66:67], v[50:51], v[110:111] op_sel_hi:[0,1,1]
	v_cvt_pk_bf16_f32 v48, v48, v49
	v_cvt_pk_bf16_f32 v49, v50, v51
	ds_write_b64 v75, v[48:49] offset:96
	v_pk_mul_f32 v[112:113], v[68:69], v[112:113] op_sel_hi:[0,1]
	v_pk_mul_f32 v[114:115], v[68:69], v[114:115] op_sel_hi:[0,1]
	v_pk_fma_f32 v[44:45], v[66:67], v[44:45], v[112:113] op_sel_hi:[0,1,1]
	v_pk_fma_f32 v[46:47], v[66:67], v[46:47], v[114:115] op_sel_hi:[0,1,1]
	v_cvt_pk_bf16_f32 v44, v44, v45
	v_cvt_pk_bf16_f32 v45, v46, v47
	ds_write_b64 v75, v[44:45] offset:128
	v_pk_mul_f32 v[116:117], v[68:69], v[116:117] op_sel_hi:[0,1]
	v_pk_mul_f32 v[118:119], v[68:69], v[118:119] op_sel_hi:[0,1]
	v_pk_fma_f32 v[40:41], v[66:67], v[40:41], v[116:117] op_sel_hi:[0,1,1]
	v_pk_fma_f32 v[42:43], v[66:67], v[42:43], v[118:119] op_sel_hi:[0,1,1]
	v_cvt_pk_bf16_f32 v40, v40, v41
	v_cvt_pk_bf16_f32 v41, v42, v43
	ds_write_b64 v75, v[40:41] offset:160
	v_pk_mul_f32 v[120:121], v[68:69], v[120:121] op_sel_hi:[0,1]
	v_pk_mul_f32 v[122:123], v[68:69], v[122:123] op_sel_hi:[0,1]
	v_pk_fma_f32 v[36:37], v[66:67], v[36:37], v[120:121] op_sel_hi:[0,1,1]
	v_pk_fma_f32 v[38:39], v[66:67], v[38:39], v[122:123] op_sel_hi:[0,1,1]
	v_cvt_pk_bf16_f32 v36, v36, v37
	v_cvt_pk_bf16_f32 v37, v38, v39
	ds_write_b64 v75, v[36:37] offset:192
	v_pk_mul_f32 v[124:125], v[68:69], v[124:125] op_sel_hi:[0,1]
	v_pk_mul_f32 v[126:127], v[68:69], v[126:127] op_sel_hi:[0,1]
	v_pk_fma_f32 v[32:33], v[66:67], v[32:33], v[124:125] op_sel_hi:[0,1,1]
	v_pk_fma_f32 v[34:35], v[66:67], v[34:35], v[126:127] op_sel_hi:[0,1,1]
	v_cvt_pk_bf16_f32 v32, v32, v33
	v_cvt_pk_bf16_f32 v33, v34, v35
	ds_write_b64 v75, v[32:33] offset:224
	v_pk_mul_f32 v[128:129], v[68:69], v[128:129] op_sel_hi:[0,1]
	v_pk_mul_f32 v[130:131], v[68:69], v[130:131] op_sel_hi:[0,1]
	v_pk_fma_f32 v[28:29], v[66:67], v[28:29], v[128:129] op_sel_hi:[0,1,1]
	v_pk_fma_f32 v[30:31], v[66:67], v[30:31], v[130:131] op_sel_hi:[0,1,1]
	v_cvt_pk_bf16_f32 v28, v28, v29
	v_cvt_pk_bf16_f32 v29, v30, v31
	ds_write_b64 v75, v[28:29] offset:256
	v_pk_mul_f32 v[132:133], v[68:69], v[132:133] op_sel_hi:[0,1]
	v_pk_mul_f32 v[134:135], v[68:69], v[134:135] op_sel_hi:[0,1]
	v_pk_fma_f32 v[24:25], v[66:67], v[24:25], v[132:133] op_sel_hi:[0,1,1]
	v_pk_fma_f32 v[26:27], v[66:67], v[26:27], v[134:135] op_sel_hi:[0,1,1]
	v_cvt_pk_bf16_f32 v24, v24, v25
	v_cvt_pk_bf16_f32 v25, v26, v27
	ds_write_b64 v75, v[24:25] offset:288
	v_pk_mul_f32 v[136:137], v[68:69], v[136:137] op_sel_hi:[0,1]
	v_pk_mul_f32 v[138:139], v[68:69], v[138:139] op_sel_hi:[0,1]
	v_pk_fma_f32 v[20:21], v[66:67], v[20:21], v[136:137] op_sel_hi:[0,1,1]
	v_pk_fma_f32 v[22:23], v[66:67], v[22:23], v[138:139] op_sel_hi:[0,1,1]
	v_cvt_pk_bf16_f32 v20, v20, v21
	v_cvt_pk_bf16_f32 v21, v22, v23
	ds_write_b64 v75, v[20:21] offset:320
	v_pk_mul_f32 v[140:141], v[68:69], v[140:141] op_sel_hi:[0,1]
	v_pk_mul_f32 v[142:143], v[68:69], v[142:143] op_sel_hi:[0,1]
	v_pk_fma_f32 v[16:17], v[66:67], v[16:17], v[140:141] op_sel_hi:[0,1,1]
	v_pk_fma_f32 v[18:19], v[66:67], v[18:19], v[142:143] op_sel_hi:[0,1,1]
	v_cvt_pk_bf16_f32 v16, v16, v17
	v_cvt_pk_bf16_f32 v17, v18, v19
	ds_write_b64 v75, v[16:17] offset:352
	v_pk_mul_f32 v[144:145], v[68:69], v[144:145] op_sel_hi:[0,1]
	v_pk_mul_f32 v[146:147], v[68:69], v[146:147] op_sel_hi:[0,1]
	v_pk_fma_f32 v[12:13], v[66:67], v[12:13], v[144:145] op_sel_hi:[0,1,1]
	v_pk_fma_f32 v[14:15], v[66:67], v[14:15], v[146:147] op_sel_hi:[0,1,1]
	v_cvt_pk_bf16_f32 v12, v12, v13
	v_cvt_pk_bf16_f32 v13, v14, v15
	ds_write_b64 v75, v[12:13] offset:384
	v_pk_mul_f32 v[148:149], v[68:69], v[148:149] op_sel_hi:[0,1]
	v_pk_mul_f32 v[150:151], v[68:69], v[150:151] op_sel_hi:[0,1]
	v_pk_fma_f32 v[8:9], v[66:67], v[8:9], v[148:149] op_sel_hi:[0,1,1]
	v_pk_fma_f32 v[10:11], v[66:67], v[10:11], v[150:151] op_sel_hi:[0,1,1]
	v_cvt_pk_bf16_f32 v8, v8, v9
	v_cvt_pk_bf16_f32 v9, v10, v11
	ds_write_b64 v75, v[8:9] offset:416
	v_pk_mul_f32 v[152:153], v[68:69], v[152:153] op_sel_hi:[0,1]
	v_pk_mul_f32 v[154:155], v[68:69], v[154:155] op_sel_hi:[0,1]
	v_pk_fma_f32 v[4:5], v[66:67], v[4:5], v[152:153] op_sel_hi:[0,1,1]
	v_pk_fma_f32 v[6:7], v[66:67], v[6:7], v[154:155] op_sel_hi:[0,1,1]
	v_cvt_pk_bf16_f32 v4, v4, v5
	v_cvt_pk_bf16_f32 v5, v6, v7
	ds_write_b64 v75, v[4:5] offset:448
	v_pk_mul_f32 v[156:157], v[68:69], v[156:157] op_sel_hi:[0,1]
	v_pk_mul_f32 v[158:159], v[68:69], v[158:159] op_sel_hi:[0,1]
	v_pk_fma_f32 v[0:1], v[66:67], v[0:1], v[156:157] op_sel_hi:[0,1,1]
	v_pk_fma_f32 v[2:3], v[66:67], v[2:3], v[158:159] op_sel_hi:[0,1,1]
	v_cvt_pk_bf16_f32 v0, v0, v1
	v_cvt_pk_bf16_f32 v1, v2, v3
	ds_write_b64 v75, v[0:1] offset:480
	s_waitcnt lgkmcnt(0)
	ds_read_b128 v[96:99], v76
	ds_read_b128 v[100:103], v76 offset:1056
	ds_read_b128 v[104:107], v76 offset:2112
	ds_read_b128 v[108:111], v76 offset:3168
	ds_read_b128 v[112:115], v76 offset:4224
	ds_read_b128 v[116:119], v76 offset:5280
	ds_read_b128 v[120:123], v76 offset:6336
	ds_read_b128 v[124:127], v76 offset:7392
	s_waitcnt lgkmcnt(7)
	global_store_dwordx4 v[64:65], v[96:99], off
	s_waitcnt lgkmcnt(6)
	global_store_dwordx4 v[64:65], v[100:103], off offset:1024
	s_waitcnt lgkmcnt(5)
	global_store_dwordx4 v[64:65], v[104:107], off offset:2048
	s_waitcnt lgkmcnt(4)
	global_store_dwordx4 v[64:65], v[108:111], off offset:3072
	s_waitcnt lgkmcnt(3)
	global_store_dwordx4 v[78:79], v[112:115], off
	s_waitcnt lgkmcnt(2)
	global_store_dwordx4 v[78:79], v[116:119], off offset:1024
	s_waitcnt lgkmcnt(1)
	global_store_dwordx4 v[78:79], v[120:123], off offset:2048
	s_waitcnt lgkmcnt(0)
	global_store_dwordx4 v[78:79], v[124:127], off offset:3072
